# up-projection output stores with the nt hint (keep operand tiles in L2)
# speedup vs baseline: 1.0148x; 1.0105x over previous
; #define PG8_STAGE(bufoff, gbase, voff) do { _Pragma("unroll") for (int _i = 0; _i < 2; ++_i) \
;         __builtin_amdgcn_global_load_lds((const unsigned*)((const char*)(gbase) + (voff)[_i]), (PG8_LAS unsigned*)(lds + (bufoff) + ldsw + _i * 8192), 16, 0, 0); } while (0)
; #define PG8_LDA(dst, b, h) do { _Pragma("unroll") for (int m = 0; m < 4; ++m) _Pragma("unroll") for (int k = 0; k < 2; ++k) dst[m][k] = *(const PG8_LAS bf16x8*)(lds + PG8_SA(b, h) + aoff + m * 2048 + k * 1024); } while (0)
; #define PG8_LDB(dst, b, h) do { _Pragma("unroll") for (int n = 0; n < 2; ++n) _Pragma("unroll") for (int k = 0; k < 2; ++k) dst[n][k] = *(const PG8_LAS bf16x8*)(lds + PG8_SB(b, h) + boff + n * 2048 + k * 1024); } while (0)
; #define PG8_SCHED __builtin_amdgcn_sched_barrier(0)
; template <class Epi, class Sched, bool ALIGN_EPI = false, bool SP2 = false>
; __device__ __forceinline__ void gemm_phase(PG8_LAS unsigned char* lds, const Gemm g, const Sched& S, const Epi& E, const int wid) {
;     ...
;             PG8_LDB(B0, 0, 0); PG8_LDB(B1, 0, 1); PG8_SCHED; PG8_LDA(At, 0, 0); PG8_STAGE(PG8_SA(1, 1), a1 + hsA, voffA);
;     __device__ __forceinline__ void operator()(const f32x4 (&acc)[2][2][4][2], const Unit& u, int wr, int wc, int fr, int fq) const {
;         const int row0 = u.pm * BM + wr * 64 + fr, col0 = u.pn * BM + wc * 32 + 8 * fq;
;         f32x4 sv[2][2];
; #pragma unroll
;         for (int bj = 0; bj < 2; ++bj)
; #pragma unroll
;             for (int n = 0; n < 2; ++n) { sv[bj][n] = cs ? *(const f32x4*)(cs + col0 + bj * HALF + 4 * n) : (f32x4){1.f, 1.f, 1.f, 1.f}; sv[bj][n] = sv[bj][n] * sc; }
; #pragma unroll
;         for (int ai = 0; ai < 2; ++ai)
; #pragma unroll
;             for (int m = 0; m < 4; ++m) { bf16_t* rowp = O + (size_t)(row0 + ai * HALF + m * 16) * ldc + col0;
; #pragma unroll
;                 for (int bj = 0; bj < 2; ++bj) { f32x4 v0 = acc[ai][bj][m][0] * sv[bj][0], v1 = acc[ai][bj][m][1] * sv[bj][1];
;                     if (ACT == 1) {
; #pragma unroll
;                         for (int e = 0; e < 4; ++e) { const float a = fmaxf(v0[e], 0.f), b = fmaxf(v1[e], 0.f); v0[e] = a * a; v1[e] = b * b; } }
;                     u32x4 w; w.x = pk2(v0[0], v0[1]); w.y = pk2(v0[2], v0[3]); w.z = pk2(v1[0], v1[1]); w.w = pk2(v1[2], v1[3]);
;                     *(u32x4*)(rowp + bj * HALF) = w; } }
.LBB0_1477:
	s_add_u32 s8, s65, 0x40080
	s_addc_u32 s9, s49, 0
	v_lshl_add_u64 v[146:147], s[8:9], 0, v[138:139]
	s_add_i32 m0, s85, 0xc000
	s_nop 0
	global_load_lds_dwordx4 v[146:147], off
	v_lshl_add_u64 v[146:147], s[8:9], 0, v[140:141]
	s_add_i32 m0, s85, 0xe000
	s_nop 0
	global_load_lds_dwordx4 v[146:147], off
	v_mbcnt_lo_u32_b32 v152, -1, 0
	v_mbcnt_hi_u32_b32 v152, -1, v152
	s_lshl_b32 s8, s64, 8
	v_ashrrev_i32_e32 v146, 1, v152
	s_or_b32 s8, s8, s76
	v_and_b32_e32 v146, -8, v146
	v_add_u32_e32 v146, s8, v146
	s_lshl_b32 s8, s54, 8
	s_add_i32 s8, s8, s29
	v_and_or_b32 v152, v152, 15, s8
	v_ashrrev_i32_e32 v153, 31, v152
	v_ashrrev_i32_e32 v147, 31, v146
	v_lshlrev_b64 v[154:155], 13, v[152:153]
	v_max_f32_e32 v122, v122, v122
	v_max_f32_e32 v123, v123, v123
	v_lshl_add_u64 v[154:155], s[14:15], 0, v[154:155]
	v_lshlrev_b64 v[156:157], 1, v[146:147]
	v_max_f32_e32 v122, 0, v122
	v_max_f32_e32 v123, 0, v123
	v_lshl_add_u64 v[146:147], v[154:155], 0, v[156:157]
	v_pk_mul_f32 v[154:155], v[122:123], v[122:123]
	v_max_f32_e32 v123, v124, v124
	v_max_f32_e32 v126, v126, v126
	v_max_f32_e32 v127, v127, v127
	v_max_f32_e32 v122, v128, v128
	v_max_f32_e32 v124, 0, v123
	v_max_f32_e32 v123, v129, v129
	v_max_f32_e32 v125, v125, v125
	v_max_f32_e32 v126, 0, v126
	v_max_f32_e32 v127, 0, v127
	v_max_f32_e32 v122, 0, v122
	v_max_f32_e32 v123, 0, v123
	v_max_f32_e32 v125, 0, v125
	v_pk_mul_f32 v[126:127], v[126:127], v[126:127]
	v_pk_mul_f32 v[128:129], v[122:123], v[122:123]
	v_pk_mul_f32 v[158:159], v[124:125], v[124:125]
	v_max_f32_e32 v114, v114, v114
	v_max_f32_e32 v115, v115, v115
	v_cvt_pk_bf16_f32 v122, v126, v127
	v_cvt_pk_bf16_f32 v123, v128, v129
	v_cvt_pk_bf16_f32 v124, v154, v155
	v_cvt_pk_bf16_f32 v125, v158, v159
	v_max_f32_e32 v114, 0, v114
	v_max_f32_e32 v115, 0, v115
	global_store_dwordx4 v[146:147], v[122:125], off nt
	v_max_f32_e32 v118, v118, v118
	v_max_f32_e32 v119, v119, v119
	v_pk_mul_f32 v[122:123], v[114:115], v[114:115]
	v_max_f32_e32 v115, v116, v116
	v_max_f32_e32 v114, v120, v120
	v_max_f32_e32 v116, 0, v115
	v_max_f32_e32 v115, v121, v121
	v_max_f32_e32 v117, v117, v117
	v_max_f32_e32 v118, 0, v118
	v_max_f32_e32 v119, 0, v119
	v_max_f32_e32 v114, 0, v114
	v_max_f32_e32 v115, 0, v115
	v_max_f32_e32 v117, 0, v117
	v_pk_mul_f32 v[118:119], v[118:119], v[118:119]
	v_pk_mul_f32 v[120:121], v[114:115], v[114:115]
	v_pk_mul_f32 v[124:125], v[116:117], v[116:117]
	v_max_f32_e32 v106, v106, v106
	v_max_f32_e32 v107, v107, v107
	v_cvt_pk_bf16_f32 v114, v118, v119
	v_cvt_pk_bf16_f32 v115, v120, v121
	v_cvt_pk_bf16_f32 v116, v122, v123
	v_cvt_pk_bf16_f32 v117, v124, v125
	v_max_f32_e32 v106, 0, v106
	v_max_f32_e32 v107, 0, v107
	global_store_dwordx4 v[146:147], v[114:117], off offset:256 nt
	v_max_f32_e32 v110, v110, v110
	v_max_f32_e32 v111, v111, v111
	v_or_b32_e32 v114, 16, v152
	v_pk_mul_f32 v[116:117], v[106:107], v[106:107]
	v_max_f32_e32 v107, v108, v108
	v_ashrrev_i32_e32 v115, 31, v114
	v_max_f32_e32 v106, v112, v112
	v_max_f32_e32 v108, 0, v107
	v_max_f32_e32 v107, v113, v113
	v_max_f32_e32 v109, v109, v109
	v_lshlrev_b64 v[114:115], 13, v[114:115]
	v_max_f32_e32 v110, 0, v110
	v_max_f32_e32 v111, 0, v111
	v_max_f32_e32 v106, 0, v106
	v_max_f32_e32 v107, 0, v107
	v_max_f32_e32 v109, 0, v109
	v_lshl_add_u64 v[114:115], s[14:15], 0, v[114:115]
	v_pk_mul_f32 v[110:111], v[110:111], v[110:111]
	v_pk_mul_f32 v[112:113], v[106:107], v[106:107]
	v_pk_mul_f32 v[118:119], v[108:109], v[108:109]
	v_max_f32_e32 v98, v98, v98
	v_max_f32_e32 v99, v99, v99
	v_lshl_add_u64 v[114:115], v[114:115], 0, v[156:157]
	v_cvt_pk_bf16_f32 v106, v110, v111
	v_cvt_pk_bf16_f32 v107, v112, v113
	v_cvt_pk_bf16_f32 v108, v116, v117
	v_cvt_pk_bf16_f32 v109, v118, v119
	v_max_f32_e32 v98, 0, v98
	v_max_f32_e32 v99, 0, v99
	global_store_dwordx4 v[114:115], v[106:109], off nt
	v_max_f32_e32 v102, v102, v102
	v_max_f32_e32 v103, v103, v103
	v_pk_mul_f32 v[106:107], v[98:99], v[98:99]
	v_max_f32_e32 v99, v100, v100
	v_max_f32_e32 v98, v104, v104
	v_max_f32_e32 v100, 0, v99
	v_max_f32_e32 v99, v105, v105
	v_max_f32_e32 v101, v101, v101
	v_max_f32_e32 v102, 0, v102
	v_max_f32_e32 v103, 0, v103
	v_max_f32_e32 v98, 0, v98
	v_max_f32_e32 v99, 0, v99
	v_max_f32_e32 v101, 0, v101
	v_pk_mul_f32 v[102:103], v[102:103], v[102:103]
	v_pk_mul_f32 v[104:105], v[98:99], v[98:99]
	v_pk_mul_f32 v[108:109], v[100:101], v[100:101]
	v_max_f32_e32 v90, v90, v90
	v_max_f32_e32 v91, v91, v91
	v_cvt_pk_bf16_f32 v98, v102, v103
	v_cvt_pk_bf16_f32 v99, v104, v105
	v_cvt_pk_bf16_f32 v100, v106, v107
	v_cvt_pk_bf16_f32 v101, v108, v109
	v_max_f32_e32 v90, 0, v90
	v_max_f32_e32 v91, 0, v91
	global_store_dwordx4 v[114:115], v[98:101], off offset:256 nt
	v_max_f32_e32 v94, v94, v94
	v_max_f32_e32 v95, v95, v95
	v_or_b32_e32 v98, 32, v152
	v_pk_mul_f32 v[100:101], v[90:91], v[90:91]
	v_max_f32_e32 v91, v92, v92
	v_ashrrev_i32_e32 v99, 31, v98
	v_max_f32_e32 v90, v96, v96
	v_max_f32_e32 v92, 0, v91
	v_max_f32_e32 v91, v97, v97
	v_max_f32_e32 v93, v93, v93
	v_lshlrev_b64 v[98:99], 13, v[98:99]
	v_max_f32_e32 v94, 0, v94
	v_max_f32_e32 v95, 0, v95
	v_max_f32_e32 v90, 0, v90
	v_max_f32_e32 v91, 0, v91
	v_max_f32_e32 v93, 0, v93
	v_lshl_add_u64 v[98:99], s[14:15], 0, v[98:99]
	v_pk_mul_f32 v[94:95], v[94:95], v[94:95]
	v_pk_mul_f32 v[96:97], v[90:91], v[90:91]
	v_pk_mul_f32 v[102:103], v[92:93], v[92:93]
	v_max_f32_e32 v82, v82, v82
	v_max_f32_e32 v83, v83, v83
	v_lshl_add_u64 v[98:99], v[98:99], 0, v[156:157]
	v_cvt_pk_bf16_f32 v90, v94, v95
	v_cvt_pk_bf16_f32 v91, v96, v97
	v_cvt_pk_bf16_f32 v92, v100, v101
	v_cvt_pk_bf16_f32 v93, v102, v103
	v_max_f32_e32 v82, 0, v82
; __device__ __forceinline__ unsigned pk2(float lo, float hi) { f32x2_t v = {lo, hi}; bf16x2_t b = __builtin_convertvector(v, bf16x2_t); return __builtin_bit_cast(unsigned, b); }
;     __device__ __forceinline__ void operator()(const f32x4 (&acc)[2][2][4][2], const Unit& u, int wr, int wc, int fr, int fq) const {
;     ...
;         for (int ai = 0; ai < 2; ++ai)
; #pragma unroll
;             for (int m = 0; m < 4; ++m) { bf16_t* rowp = O + (size_t)(row0 + ai * HALF + m * 16) * ldc + col0;
; #pragma unroll
;                 for (int bj = 0; bj < 2; ++bj) { f32x4 v0 = acc[ai][bj][m][0] * sv[bj][0], v1 = acc[ai][bj][m][1] * sv[bj][1];
;                     if (ACT == 1) {
; #pragma unroll
;                         for (int e = 0; e < 4; ++e) { const float a = fmaxf(v0[e], 0.f), b = fmaxf(v1[e], 0.f); v0[e] = a * a; v1[e] = b * b; } }
;                     u32x4 w; w.x = pk2(v0[0], v0[1]); w.y = pk2(v0[2], v0[3]); w.z = pk2(v1[0], v1[1]); w.w = pk2(v1[2], v1[3]);
;                     *(u32x4*)(rowp + bj * HALF) = w; } }
	v_max_f32_e32 v83, 0, v83
	global_store_dwordx4 v[98:99], v[90:93], off nt
	v_max_f32_e32 v86, v86, v86
	v_max_f32_e32 v87, v87, v87
	v_pk_mul_f32 v[90:91], v[82:83], v[82:83]
	v_max_f32_e32 v83, v84, v84
	v_max_f32_e32 v82, v88, v88
	v_max_f32_e32 v84, 0, v83
	v_max_f32_e32 v83, v89, v89
	v_max_f32_e32 v85, v85, v85
	v_max_f32_e32 v86, 0, v86
	v_max_f32_e32 v87, 0, v87
	v_max_f32_e32 v82, 0, v82
	v_max_f32_e32 v83, 0, v83
	v_max_f32_e32 v85, 0, v85
	v_pk_mul_f32 v[86:87], v[86:87], v[86:87]
	v_pk_mul_f32 v[88:89], v[82:83], v[82:83]
	v_pk_mul_f32 v[92:93], v[84:85], v[84:85]
	v_max_f32_e32 v74, v74, v74
	v_max_f32_e32 v75, v75, v75
	v_cvt_pk_bf16_f32 v82, v86, v87
	v_cvt_pk_bf16_f32 v83, v88, v89
	v_cvt_pk_bf16_f32 v84, v90, v91
	v_cvt_pk_bf16_f32 v85, v92, v93
	v_max_f32_e32 v74, 0, v74
	v_max_f32_e32 v75, 0, v75
	global_store_dwordx4 v[98:99], v[82:85], off offset:256 nt
	v_max_f32_e32 v78, v78, v78
	v_max_f32_e32 v79, v79, v79
	v_or_b32_e32 v82, 48, v152
	v_pk_mul_f32 v[84:85], v[74:75], v[74:75]
	v_max_f32_e32 v75, v76, v76
	v_ashrrev_i32_e32 v83, 31, v82
	v_max_f32_e32 v74, v80, v80
	v_max_f32_e32 v76, 0, v75
	v_max_f32_e32 v75, v81, v81
	v_max_f32_e32 v77, v77, v77
	v_lshlrev_b64 v[82:83], 13, v[82:83]
	v_max_f32_e32 v78, 0, v78
	v_max_f32_e32 v79, 0, v79
	v_max_f32_e32 v74, 0, v74
	v_max_f32_e32 v75, 0, v75
	v_max_f32_e32 v77, 0, v77
	v_lshl_add_u64 v[82:83], s[14:15], 0, v[82:83]
	v_pk_mul_f32 v[78:79], v[78:79], v[78:79]
	v_pk_mul_f32 v[80:81], v[74:75], v[74:75]
	v_pk_mul_f32 v[86:87], v[76:77], v[76:77]
	v_max_f32_e32 v66, v66, v66
	v_max_f32_e32 v67, v67, v67
	v_lshl_add_u64 v[82:83], v[82:83], 0, v[156:157]
	v_cvt_pk_bf16_f32 v74, v78, v79
	v_cvt_pk_bf16_f32 v75, v80, v81
	v_cvt_pk_bf16_f32 v76, v84, v85
	v_cvt_pk_bf16_f32 v77, v86, v87
	v_max_f32_e32 v66, 0, v66
	v_max_f32_e32 v67, 0, v67
	global_store_dwordx4 v[82:83], v[74:77], off nt
	v_max_f32_e32 v70, v70, v70
	v_max_f32_e32 v71, v71, v71
	v_pk_mul_f32 v[74:75], v[66:67], v[66:67]
	v_max_f32_e32 v67, v68, v68
	v_max_f32_e32 v66, v72, v72
	v_max_f32_e32 v68, 0, v67
	v_max_f32_e32 v67, v73, v73
	v_max_f32_e32 v69, v69, v69
	v_max_f32_e32 v70, 0, v70
	v_max_f32_e32 v71, 0, v71
	v_max_f32_e32 v66, 0, v66
	v_max_f32_e32 v67, 0, v67
	v_max_f32_e32 v69, 0, v69
	v_pk_mul_f32 v[70:71], v[70:71], v[70:71]
	v_pk_mul_f32 v[72:73], v[66:67], v[66:67]
	v_pk_mul_f32 v[76:77], v[68:69], v[68:69]
	v_max_f32_e32 v58, v58, v58
	v_max_f32_e32 v59, v59, v59
	v_cvt_pk_bf16_f32 v66, v70, v71
	v_cvt_pk_bf16_f32 v67, v72, v73
	v_cvt_pk_bf16_f32 v68, v74, v75
	v_cvt_pk_bf16_f32 v69, v76, v77
	v_max_f32_e32 v58, 0, v58
	v_max_f32_e32 v59, 0, v59
	global_store_dwordx4 v[82:83], v[66:69], off offset:256 nt
	v_max_f32_e32 v62, v62, v62
	v_max_f32_e32 v63, v63, v63
	v_pk_mul_f32 v[68:69], v[58:59], v[58:59]
	v_max_f32_e32 v59, v60, v60
	v_max_f32_e32 v62, 0, v62
	v_max_f32_e32 v63, 0, v63
	v_max_f32_e32 v58, v64, v64
	v_max_f32_e32 v60, 0, v59
	v_max_f32_e32 v59, v65, v65
	v_max_f32_e32 v61, v61, v61
	v_pk_mul_f32 v[62:63], v[62:63], v[62:63]
	v_max_f32_e32 v58, 0, v58
	v_max_f32_e32 v59, 0, v59
	v_max_f32_e32 v61, 0, v61
	v_pk_mul_f32 v[64:65], v[58:59], v[58:59]
	v_pk_mul_f32 v[70:71], v[60:61], v[60:61]
	v_cvt_pk_bf16_f32 v58, v62, v63
	v_add_co_u32_e32 v62, vcc, s37, v146
	v_max_f32_e32 v50, v50, v50
	v_max_f32_e32 v51, v51, v51
	v_cvt_pk_bf16_f32 v59, v64, v65
	v_cvt_pk_bf16_f32 v60, v68, v69
	v_cvt_pk_bf16_f32 v61, v70, v71
	v_addc_co_u32_e32 v63, vcc, 0, v147, vcc
	v_max_f32_e32 v50, 0, v50
	v_max_f32_e32 v51, 0, v51
	global_store_dwordx4 v[62:63], v[58:61], off nt
	v_max_f32_e32 v54, v54, v54
	v_max_f32_e32 v55, v55, v55
	v_pk_mul_f32 v[58:59], v[50:51], v[50:51]
	v_max_f32_e32 v51, v52, v52
	v_max_f32_e32 v50, v56, v56
	v_max_f32_e32 v52, 0, v51
	v_max_f32_e32 v51, v57, v57
	v_max_f32_e32 v53, v53, v53
	v_max_f32_e32 v54, 0, v54
	v_max_f32_e32 v55, 0, v55
	v_max_f32_e32 v50, 0, v50
	v_max_f32_e32 v51, 0, v51
	v_max_f32_e32 v53, 0, v53
	v_pk_mul_f32 v[54:55], v[54:55], v[54:55]
	v_pk_mul_f32 v[56:57], v[50:51], v[50:51]
	v_pk_mul_f32 v[60:61], v[52:53], v[52:53]
	v_max_f32_e32 v42, v42, v42
	v_max_f32_e32 v43, v43, v43
	v_lshl_add_u64 v[66:67], v[146:147], 0, s[38:39]
	v_cvt_pk_bf16_f32 v50, v54, v55
	v_cvt_pk_bf16_f32 v51, v56, v57
	v_cvt_pk_bf16_f32 v52, v58, v59
	v_cvt_pk_bf16_f32 v53, v60, v61
	v_max_f32_e32 v42, 0, v42
	v_max_f32_e32 v43, 0, v43
	global_store_dwordx4 v[66:67], v[50:53], off offset:256 nt
	v_max_f32_e32 v46, v46, v46
	v_max_f32_e32 v47, v47, v47
	v_pk_mul_f32 v[52:53], v[42:43], v[42:43]
	v_max_f32_e32 v43, v44, v44
	v_max_f32_e32 v46, 0, v46
	v_max_f32_e32 v47, 0, v47
	v_max_f32_e32 v42, v48, v48
	v_max_f32_e32 v44, 0, v43
	v_max_f32_e32 v43, v49, v49
	v_max_f32_e32 v45, v45, v45
	v_pk_mul_f32 v[46:47], v[46:47], v[46:47]
	v_max_f32_e32 v42, 0, v42
	v_max_f32_e32 v43, 0, v43
	v_max_f32_e32 v45, 0, v45
; #define PG8_BAR __builtin_amdgcn_s_barrier()
; __device__ __forceinline__ unsigned pk2(float lo, float hi) { f32x2_t v = {lo, hi}; bf16x2_t b = __builtin_convertvector(v, bf16x2_t); return __builtin_bit_cast(unsigned, b); }
; template <class Epi, class Sched, bool ALIGN_EPI = false, bool SP2 = false>
; __device__ __forceinline__ void gemm_phase(PG8_LAS unsigned char* lds, const Gemm g, const Sched& S, const Epi& E, const int wid) {
;     ...
;         cur = nxt; cA = nA; cB = nB; ++ui;
;         if constexpr (ALIGN_EPI) { if (wr == 1) PG8_BAR; }
;     }
;     __device__ __forceinline__ void operator()(const f32x4 (&acc)[2][2][4][2], const Unit& u, int wr, int wc, int fr, int fq) const {
;     ...
;         for (int ai = 0; ai < 2; ++ai)
; #pragma unroll
;             for (int m = 0; m < 4; ++m) { bf16_t* rowp = O + (size_t)(row0 + ai * HALF + m * 16) * ldc + col0;
; #pragma unroll
;                 for (int bj = 0; bj < 2; ++bj) { f32x4 v0 = acc[ai][bj][m][0] * sv[bj][0], v1 = acc[ai][bj][m][1] * sv[bj][1];
;                     if (ACT == 1) {
; #pragma unroll
;                         for (int e = 0; e < 4; ++e) { const float a = fmaxf(v0[e], 0.f), b = fmaxf(v1[e], 0.f); v0[e] = a * a; v1[e] = b * b; } }
;                     u32x4 w; w.x = pk2(v0[0], v0[1]); w.y = pk2(v0[2], v0[3]); w.z = pk2(v1[0], v1[1]); w.w = pk2(v1[2], v1[3]);
;                     *(u32x4*)(rowp + bj * HALF) = w; } }
	v_pk_mul_f32 v[48:49], v[42:43], v[42:43]
	v_pk_mul_f32 v[54:55], v[44:45], v[44:45]
	v_cvt_pk_bf16_f32 v42, v46, v47
	v_add_co_u32_e32 v46, vcc, s55, v146
	v_max_f32_e32 v34, v34, v34
	v_max_f32_e32 v35, v35, v35
	v_cvt_pk_bf16_f32 v43, v48, v49
	v_cvt_pk_bf16_f32 v44, v52, v53
	v_cvt_pk_bf16_f32 v45, v54, v55
	v_addc_co_u32_e32 v47, vcc, 0, v147, vcc
	v_max_f32_e32 v34, 0, v34
	v_max_f32_e32 v35, 0, v35
	global_store_dwordx4 v[46:47], v[42:45], off nt
	v_max_f32_e32 v38, v38, v38
	v_max_f32_e32 v39, v39, v39
	v_pk_mul_f32 v[42:43], v[34:35], v[34:35]
	v_max_f32_e32 v35, v36, v36
	v_max_f32_e32 v34, v40, v40
	v_max_f32_e32 v36, 0, v35
	v_max_f32_e32 v35, v41, v41
	v_max_f32_e32 v37, v37, v37
	v_max_f32_e32 v38, 0, v38
	v_max_f32_e32 v39, 0, v39
	v_max_f32_e32 v34, 0, v34
	v_max_f32_e32 v35, 0, v35
	v_max_f32_e32 v37, 0, v37
	v_pk_mul_f32 v[38:39], v[38:39], v[38:39]
	v_pk_mul_f32 v[40:41], v[34:35], v[34:35]
	v_pk_mul_f32 v[44:45], v[36:37], v[36:37]
	v_max_f32_e32 v26, v26, v26
	v_max_f32_e32 v27, v27, v27
	v_lshl_add_u64 v[50:51], v[146:147], 0, s[40:41]
	v_cvt_pk_bf16_f32 v34, v38, v39
	v_cvt_pk_bf16_f32 v35, v40, v41
	v_cvt_pk_bf16_f32 v36, v42, v43
	v_cvt_pk_bf16_f32 v37, v44, v45
	v_max_f32_e32 v26, 0, v26
	v_max_f32_e32 v27, 0, v27
	global_store_dwordx4 v[50:51], v[34:37], off offset:256 nt
	v_max_f32_e32 v30, v30, v30
	v_max_f32_e32 v31, v31, v31
	v_pk_mul_f32 v[36:37], v[26:27], v[26:27]
	v_max_f32_e32 v27, v28, v28
	v_max_f32_e32 v30, 0, v30
	v_max_f32_e32 v31, 0, v31
	v_max_f32_e32 v26, v32, v32
	v_max_f32_e32 v28, 0, v27
	v_max_f32_e32 v27, v33, v33
	v_max_f32_e32 v29, v29, v29
	v_pk_mul_f32 v[30:31], v[30:31], v[30:31]
	v_max_f32_e32 v26, 0, v26
	v_max_f32_e32 v27, 0, v27
	v_max_f32_e32 v29, 0, v29
	v_pk_mul_f32 v[32:33], v[26:27], v[26:27]
	v_pk_mul_f32 v[38:39], v[28:29], v[28:29]
	v_cvt_pk_bf16_f32 v26, v30, v31
	v_add_co_u32_e32 v30, vcc, s62, v146
	v_max_f32_e32 v18, v18, v18
	v_max_f32_e32 v19, v19, v19
	v_cvt_pk_bf16_f32 v27, v32, v33
	v_cvt_pk_bf16_f32 v28, v36, v37
	v_cvt_pk_bf16_f32 v29, v38, v39
	v_addc_co_u32_e32 v31, vcc, 0, v147, vcc
	v_max_f32_e32 v18, 0, v18
	v_max_f32_e32 v19, 0, v19
	global_store_dwordx4 v[30:31], v[26:29], off nt
	v_max_f32_e32 v22, v22, v22
	v_max_f32_e32 v23, v23, v23
	v_pk_mul_f32 v[26:27], v[18:19], v[18:19]
	v_max_f32_e32 v19, v20, v20
	v_max_f32_e32 v18, v24, v24
	v_max_f32_e32 v20, 0, v19
	v_max_f32_e32 v19, v25, v25
	v_max_f32_e32 v21, v21, v21
	v_max_f32_e32 v22, 0, v22
	v_max_f32_e32 v23, 0, v23
	v_max_f32_e32 v18, 0, v18
	v_max_f32_e32 v19, 0, v19
	v_max_f32_e32 v21, 0, v21
	v_pk_mul_f32 v[22:23], v[22:23], v[22:23]
	v_pk_mul_f32 v[24:25], v[18:19], v[18:19]
	v_pk_mul_f32 v[28:29], v[20:21], v[20:21]
	v_max_f32_e32 v10, v10, v10
	v_max_f32_e32 v11, v11, v11
	v_lshl_add_u64 v[34:35], v[146:147], 0, s[42:43]
	v_cvt_pk_bf16_f32 v18, v22, v23
	v_cvt_pk_bf16_f32 v19, v24, v25
	v_cvt_pk_bf16_f32 v20, v26, v27
	v_cvt_pk_bf16_f32 v21, v28, v29
	v_max_f32_e32 v10, 0, v10
	v_max_f32_e32 v11, 0, v11
	global_store_dwordx4 v[34:35], v[18:21], off offset:256 nt
	v_max_f32_e32 v14, v14, v14
	v_max_f32_e32 v15, v15, v15
	v_pk_mul_f32 v[20:21], v[10:11], v[10:11]
	v_max_f32_e32 v11, v12, v12
	v_max_f32_e32 v14, 0, v14
	v_max_f32_e32 v15, 0, v15
	v_max_f32_e32 v10, v16, v16
	v_max_f32_e32 v12, 0, v11
	v_max_f32_e32 v11, v17, v17
	v_max_f32_e32 v13, v13, v13
	v_pk_mul_f32 v[14:15], v[14:15], v[14:15]
	v_max_f32_e32 v10, 0, v10
	v_max_f32_e32 v11, 0, v11
	v_max_f32_e32 v13, 0, v13
	v_pk_mul_f32 v[16:17], v[10:11], v[10:11]
	v_pk_mul_f32 v[22:23], v[12:13], v[12:13]
	v_cvt_pk_bf16_f32 v10, v14, v15
	v_add_co_u32_e32 v14, vcc, s63, v146
	v_max_f32_e32 v2, v2, v2
	v_max_f32_e32 v3, v3, v3
	v_cvt_pk_bf16_f32 v11, v16, v17
	v_cvt_pk_bf16_f32 v12, v20, v21
	v_cvt_pk_bf16_f32 v13, v22, v23
	v_addc_co_u32_e32 v15, vcc, 0, v147, vcc
	v_max_f32_e32 v2, 0, v2
	v_max_f32_e32 v3, 0, v3
	global_store_dwordx4 v[14:15], v[10:13], off nt
	v_max_f32_e32 v6, v6, v6
	v_max_f32_e32 v7, v7, v7
	v_pk_mul_f32 v[10:11], v[2:3], v[2:3]
	v_max_f32_e32 v3, v4, v4
	v_max_f32_e32 v2, v8, v8
	v_max_f32_e32 v4, 0, v3
	v_max_f32_e32 v3, v9, v9
	v_max_f32_e32 v5, v5, v5
	v_max_f32_e32 v6, 0, v6
	v_max_f32_e32 v7, 0, v7
	v_max_f32_e32 v2, 0, v2
	v_max_f32_e32 v3, 0, v3
	v_max_f32_e32 v5, 0, v5
	v_pk_mul_f32 v[6:7], v[6:7], v[6:7]
	v_pk_mul_f32 v[8:9], v[2:3], v[2:3]
	v_pk_mul_f32 v[12:13], v[4:5], v[4:5]
	v_lshl_add_u64 v[18:19], v[146:147], 0, s[44:45]
	v_cvt_pk_bf16_f32 v2, v6, v7
	v_cvt_pk_bf16_f32 v3, v8, v9
	v_cvt_pk_bf16_f32 v4, v10, v11
	v_cvt_pk_bf16_f32 v5, v12, v13
	s_andn2_b64 vcc, exec, s[12:13]
	s_mov_b64 s[12:13], -1
	global_store_dwordx4 v[18:19], v[2:5], off offset:256 nt
	s_cbranch_vccnz .LBB0_1470
	v_readlane_b32 s8, v237, 4
	v_readlane_b32 s9, v237, 5
	s_and_b64 vcc, exec, s[8:9]
	s_cbranch_vccnz .LBB0_1469
	s_barrier
	s_branch .LBB0_1469
